# attention tile-A max path: the s_mov_b64 that followed the two max3 moved into the MFMA wait-state window (s_nop 3 -> s_mov + s_nop 2), 8 sites
# speedup vs baseline: 1.0051x; 1.0051x over previous
; __device__ __forceinline__ void attn_item(const Params& p, unsigned char* lds, int item) {
;     ...
;         for (int ch = 0; ch < 8; ++ch) if (2 * ch < nkt) {
;             f32x4 sA[2], sB[2];
; #pragma unroll
;             for (int k4 = 0; k4 < 2; ++k4) { sA[k4] = (f32x4){0.f, 0.f, 0.f, 0.f}; sB[k4] = (f32x4){0.f, 0.f, 0.f, 0.f};
;                 if (2 * ch + k4 < nkt) { const unsigned char* ka = lds + AT_K + (16 * (2 * ch + k4) + qi) * 272 + 16 * g4;
; #pragma unroll
;                     for (int s = 0; s < 4; ++s) { const bf16x8 a = *(const bf16x8*)(ka + 64 * s);
;                         sA[k4] = __builtin_amdgcn_mfma_f32_16x16x32_bf16(a, bqA[s], sA[k4], 0, 0, 0); sB[k4] = __builtin_amdgcn_mfma_f32_16x16x32_bf16(a, bqB[s], sB[k4], 0, 0, 0); } } }
.LBB0_385:
	ds_read_b128 v[68:71], v214
	ds_read_b128 v[72:75], v214 offset:64
	s_xor_b64 s[12:13], s[12:13], -1
	v_cndmask_b32_e64 v0, 0, 1, s[12:13]
	s_mov_b64 s[18:19], -1
	s_waitcnt lgkmcnt(0)
	v_mfma_f32_16x16x32_bf16 v[76:79], v[68:71], v[64:67], 0
	v_cmp_ne_u32_e64 s[6:7], 1, v0
	s_andn2_b64 vcc, exec, s[12:13]
	v_mfma_f32_16x16x32_bf16 v[68:71], v[68:71], v[56:59], 0
	v_mfma_f32_16x16x32_bf16 v[76:79], v[72:75], v[60:63], v[76:79]
	v_mfma_f32_16x16x32_bf16 v[68:71], v[72:75], v[52:55], v[68:71]
	ds_read_b128 v[72:75], v214 offset:128
	ds_read_b128 v[80:83], v214 offset:192
	s_waitcnt lgkmcnt(1)
	v_mfma_f32_16x16x32_bf16 v[76:79], v[72:75], v[48:51], v[76:79]
	v_mfma_f32_16x16x32_bf16 v[68:71], v[72:75], v[40:43], v[68:71]
	s_waitcnt lgkmcnt(0)
	v_mfma_f32_16x16x32_bf16 v[76:79], v[80:83], v[44:47], v[76:79]
	v_mfma_f32_16x16x32_bf16 v[68:71], v[80:83], v[36:39], v[68:71]
	ds_read_b128 v[72:75], v214 offset:4352
	ds_read_b128 v[80:83], v214 offset:4416
	s_waitcnt lgkmcnt(1)
	v_mfma_f32_16x16x32_bf16 v[84:87], v[72:75], v[64:67], 0
	v_mfma_f32_16x16x32_bf16 v[72:75], v[72:75], v[56:59], 0
	s_waitcnt lgkmcnt(0)
	v_mfma_f32_16x16x32_bf16 v[84:87], v[80:83], v[60:63], v[84:87]
	v_mfma_f32_16x16x32_bf16 v[72:75], v[80:83], v[52:55], v[72:75]
	ds_read_b128 v[80:83], v214 offset:4480
	ds_read_b128 v[92:95], v214 offset:4544
	s_waitcnt lgkmcnt(1)
	v_mfma_f32_16x16x32_bf16 v[84:87], v[80:83], v[48:51], v[84:87]
	v_mfma_f32_16x16x32_bf16 v[72:75], v[80:83], v[40:43], v[72:75]
	s_waitcnt lgkmcnt(0)
	v_mfma_f32_16x16x32_bf16 v[80:83], v[92:95], v[44:47], v[84:87]
	v_mfma_f32_16x16x32_bf16 v[72:75], v[92:95], v[36:39], v[72:75]
	s_cbranch_vccnz .LBB0_387
	v_max3_f32 v0, v76, v77, v78
	v_max3_f32 v0, v0, v79, s95
	s_mov_b64 s[18:19], 0
	s_nop 2
	v_max3_f32 v2, v80, v81, v82
	v_max3_f32 v91, v0, v2, v83

; __device__ __forceinline__ void attn_item(const Params& p, unsigned char* lds, int item) {
;     ...
;         for (int ch = 0; ch < 8; ++ch) if (2 * ch < nkt) {
;             f32x4 sA[2], sB[2];
; #pragma unroll
;             for (int k4 = 0; k4 < 2; ++k4) { sA[k4] = (f32x4){0.f, 0.f, 0.f, 0.f}; sB[k4] = (f32x4){0.f, 0.f, 0.f, 0.f};
;                 if (2 * ch + k4 < nkt) { const unsigned char* ka = lds + AT_K + (16 * (2 * ch + k4) + qi) * 272 + 16 * g4;
; #pragma unroll
;                     for (int s = 0; s < 4; ++s) { const bf16x8 a = *(const bf16x8*)(ka + 64 * s);
;                         sA[k4] = __builtin_amdgcn_mfma_f32_16x16x32_bf16(a, bqA[s], sA[k4], 0, 0, 0); sB[k4] = __builtin_amdgcn_mfma_f32_16x16x32_bf16(a, bqB[s], sB[k4], 0, 0, 0); } } }
.LBB0_406:
	ds_read_b128 v[132:135], v206 offset:8704
	ds_read_b128 v[136:139], v206 offset:8768
	s_mov_b64 s[14:15], -1
	s_and_b64 vcc, exec, s[6:7]
	s_waitcnt lgkmcnt(1)
	v_mfma_f32_16x16x32_bf16 v[140:143], v[132:135], v[64:67], 0
	v_mfma_f32_16x16x32_bf16 v[132:135], v[132:135], v[56:59], 0
	s_waitcnt lgkmcnt(0)
	v_mfma_f32_16x16x32_bf16 v[140:143], v[136:139], v[60:63], v[140:143]
	v_mfma_f32_16x16x32_bf16 v[132:135], v[136:139], v[52:55], v[132:135]
	ds_read_b128 v[136:139], v206 offset:8832
	ds_read_b128 v[144:147], v206 offset:8896
	s_waitcnt lgkmcnt(1)
	v_mfma_f32_16x16x32_bf16 v[140:143], v[136:139], v[48:51], v[140:143]
	v_mfma_f32_16x16x32_bf16 v[132:135], v[136:139], v[40:43], v[132:135]
	s_waitcnt lgkmcnt(0)
	v_mfma_f32_16x16x32_bf16 v[140:143], v[144:147], v[44:47], v[140:143]
	v_mfma_f32_16x16x32_bf16 v[132:135], v[144:147], v[36:39], v[132:135]
	ds_read_b128 v[136:139], v206 offset:13056
	ds_read_b128 v[144:147], v206 offset:13120
	s_waitcnt lgkmcnt(1)
	v_mfma_f32_16x16x32_bf16 v[188:191], v[136:139], v[64:67], 0
	v_mfma_f32_16x16x32_bf16 v[136:139], v[136:139], v[56:59], 0
	s_waitcnt lgkmcnt(0)
	v_mfma_f32_16x16x32_bf16 v[188:191], v[144:147], v[60:63], v[188:191]
	v_mfma_f32_16x16x32_bf16 v[136:139], v[144:147], v[52:55], v[136:139]
	ds_read_b128 v[144:147], v206 offset:13184
	ds_read_b128 v[244:247], v206 offset:13248
	s_waitcnt lgkmcnt(1)
	v_mfma_f32_16x16x32_bf16 v[188:191], v[144:147], v[48:51], v[188:191]
	v_mfma_f32_16x16x32_bf16 v[136:139], v[144:147], v[40:43], v[136:139]
	s_waitcnt lgkmcnt(0)
	v_mfma_f32_16x16x32_bf16 v[144:147], v[244:247], v[44:47], v[188:191]
	v_mfma_f32_16x16x32_bf16 v[136:139], v[244:247], v[36:39], v[136:139]
	s_cbranch_vccnz .LBB0_408
	v_max3_f32 v2, v140, v141, v142
	v_max3_f32 v2, v2, v143, s95
	s_mov_b64 s[14:15], 0
	s_nop 2
	v_max3_f32 v3, v144, v145, v146
	v_max3_f32 v243, v2, v3, v147

; __device__ __forceinline__ void attn_item(const Params& p, unsigned char* lds, int item) {
;     ...
;         for (int ch = 0; ch < 8; ++ch) if (2 * ch < nkt) {
;             f32x4 sA[2], sB[2];
; #pragma unroll
;             for (int k4 = 0; k4 < 2; ++k4) { sA[k4] = (f32x4){0.f, 0.f, 0.f, 0.f}; sB[k4] = (f32x4){0.f, 0.f, 0.f, 0.f};
;                 if (2 * ch + k4 < nkt) { const unsigned char* ka = lds + AT_K + (16 * (2 * ch + k4) + qi) * 272 + 16 * g4;
; #pragma unroll
;                     for (int s = 0; s < 4; ++s) { const bf16x8 a = *(const bf16x8*)(ka + 64 * s);
;                         sA[k4] = __builtin_amdgcn_mfma_f32_16x16x32_bf16(a, bqA[s], sA[k4], 0, 0, 0); sB[k4] = __builtin_amdgcn_mfma_f32_16x16x32_bf16(a, bqB[s], sB[k4], 0, 0, 0); } } }
.LBB0_425:
	ds_read_b128 v[132:135], v206 offset:17408
	ds_read_b128 v[136:139], v206 offset:17472
	s_mov_b64 s[14:15], -1
	s_and_b64 vcc, exec, s[6:7]
	s_waitcnt lgkmcnt(1)
	v_mfma_f32_16x16x32_bf16 v[140:143], v[132:135], v[64:67], 0
	v_mfma_f32_16x16x32_bf16 v[132:135], v[132:135], v[56:59], 0
	s_waitcnt lgkmcnt(0)
	v_mfma_f32_16x16x32_bf16 v[140:143], v[136:139], v[60:63], v[140:143]
	v_mfma_f32_16x16x32_bf16 v[132:135], v[136:139], v[52:55], v[132:135]
	ds_read_b128 v[136:139], v206 offset:17536
	ds_read_b128 v[144:147], v206 offset:17600
	s_waitcnt lgkmcnt(1)
	v_mfma_f32_16x16x32_bf16 v[140:143], v[136:139], v[48:51], v[140:143]
	v_mfma_f32_16x16x32_bf16 v[132:135], v[136:139], v[40:43], v[132:135]
	s_waitcnt lgkmcnt(0)
	v_mfma_f32_16x16x32_bf16 v[140:143], v[144:147], v[44:47], v[140:143]
	v_mfma_f32_16x16x32_bf16 v[132:135], v[144:147], v[36:39], v[132:135]
	ds_read_b128 v[136:139], v206 offset:21760
	ds_read_b128 v[144:147], v206 offset:21824
	s_waitcnt lgkmcnt(1)
	v_mfma_f32_16x16x32_bf16 v[188:191], v[136:139], v[64:67], 0
	v_mfma_f32_16x16x32_bf16 v[136:139], v[136:139], v[56:59], 0
	s_waitcnt lgkmcnt(0)
	v_mfma_f32_16x16x32_bf16 v[188:191], v[144:147], v[60:63], v[188:191]
	v_mfma_f32_16x16x32_bf16 v[136:139], v[144:147], v[52:55], v[136:139]
	ds_read_b128 v[144:147], v206 offset:21888
	ds_read_b128 v[244:247], v206 offset:21952
	s_waitcnt lgkmcnt(1)
	v_mfma_f32_16x16x32_bf16 v[188:191], v[144:147], v[48:51], v[188:191]
	v_mfma_f32_16x16x32_bf16 v[136:139], v[144:147], v[40:43], v[136:139]
	s_waitcnt lgkmcnt(0)
	v_mfma_f32_16x16x32_bf16 v[144:147], v[244:247], v[44:47], v[188:191]
	v_mfma_f32_16x16x32_bf16 v[136:139], v[244:247], v[36:39], v[136:139]
	s_cbranch_vccnz .LBB0_427
	v_max3_f32 v2, v140, v141, v142
	v_max3_f32 v2, v2, v143, s95
	s_mov_b64 s[14:15], 0
	s_nop 2
	v_max3_f32 v3, v144, v145, v146
	v_max3_f32 v243, v2, v3, v147

; __device__ __forceinline__ void attn_item(const Params& p, unsigned char* lds, int item) {
;     ...
;         for (int ch = 0; ch < 8; ++ch) if (2 * ch < nkt) {
;             f32x4 sA[2], sB[2];
; #pragma unroll
;             for (int k4 = 0; k4 < 2; ++k4) { sA[k4] = (f32x4){0.f, 0.f, 0.f, 0.f}; sB[k4] = (f32x4){0.f, 0.f, 0.f, 0.f};
;                 if (2 * ch + k4 < nkt) { const unsigned char* ka = lds + AT_K + (16 * (2 * ch + k4) + qi) * 272 + 16 * g4;
; #pragma unroll
;                     for (int s = 0; s < 4; ++s) { const bf16x8 a = *(const bf16x8*)(ka + 64 * s);
;                         sA[k4] = __builtin_amdgcn_mfma_f32_16x16x32_bf16(a, bqA[s], sA[k4], 0, 0, 0); sB[k4] = __builtin_amdgcn_mfma_f32_16x16x32_bf16(a, bqB[s], sB[k4], 0, 0, 0); } } }
.LBB0_444:
	ds_read_b128 v[132:135], v206 offset:26112
	ds_read_b128 v[136:139], v206 offset:26176
	s_mov_b64 s[14:15], -1
	s_and_b64 vcc, exec, s[6:7]
	s_waitcnt lgkmcnt(1)
	v_mfma_f32_16x16x32_bf16 v[140:143], v[132:135], v[64:67], 0
	v_mfma_f32_16x16x32_bf16 v[132:135], v[132:135], v[56:59], 0
	s_waitcnt lgkmcnt(0)
	v_mfma_f32_16x16x32_bf16 v[140:143], v[136:139], v[60:63], v[140:143]
	v_mfma_f32_16x16x32_bf16 v[132:135], v[136:139], v[52:55], v[132:135]
	ds_read_b128 v[136:139], v206 offset:26240
	ds_read_b128 v[144:147], v206 offset:26304
	s_waitcnt lgkmcnt(1)
	v_mfma_f32_16x16x32_bf16 v[140:143], v[136:139], v[48:51], v[140:143]
	v_mfma_f32_16x16x32_bf16 v[132:135], v[136:139], v[40:43], v[132:135]
	s_waitcnt lgkmcnt(0)
	v_mfma_f32_16x16x32_bf16 v[140:143], v[144:147], v[44:47], v[140:143]
	v_mfma_f32_16x16x32_bf16 v[132:135], v[144:147], v[36:39], v[132:135]
	ds_read_b128 v[136:139], v206 offset:30464
	ds_read_b128 v[144:147], v206 offset:30528
	s_waitcnt lgkmcnt(1)
	v_mfma_f32_16x16x32_bf16 v[188:191], v[136:139], v[64:67], 0
	v_mfma_f32_16x16x32_bf16 v[136:139], v[136:139], v[56:59], 0
	s_waitcnt lgkmcnt(0)
	v_mfma_f32_16x16x32_bf16 v[188:191], v[144:147], v[60:63], v[188:191]
	v_mfma_f32_16x16x32_bf16 v[136:139], v[144:147], v[52:55], v[136:139]
	ds_read_b128 v[144:147], v206 offset:30592
	ds_read_b128 v[244:247], v206 offset:30656
	s_waitcnt lgkmcnt(1)
	v_mfma_f32_16x16x32_bf16 v[188:191], v[144:147], v[48:51], v[188:191]
	v_mfma_f32_16x16x32_bf16 v[136:139], v[144:147], v[40:43], v[136:139]
	s_waitcnt lgkmcnt(0)
	v_mfma_f32_16x16x32_bf16 v[144:147], v[244:247], v[44:47], v[188:191]
	v_mfma_f32_16x16x32_bf16 v[136:139], v[244:247], v[36:39], v[136:139]
	s_cbranch_vccnz .LBB0_446
	v_max3_f32 v2, v140, v141, v142
	v_max3_f32 v2, v2, v143, s95
	s_mov_b64 s[14:15], 0
	s_nop 2
	v_max3_f32 v3, v144, v145, v146
	v_max3_f32 v243, v2, v3, v147

; __device__ __forceinline__ void attn_item(const Params& p, unsigned char* lds, int item) {
;     ...
;         for (int ch = 0; ch < 8; ++ch) if (2 * ch < nkt) {
;             f32x4 sA[2], sB[2];
; #pragma unroll
;             for (int k4 = 0; k4 < 2; ++k4) { sA[k4] = (f32x4){0.f, 0.f, 0.f, 0.f}; sB[k4] = (f32x4){0.f, 0.f, 0.f, 0.f};
;                 if (2 * ch + k4 < nkt) { const unsigned char* ka = lds + AT_K + (16 * (2 * ch + k4) + qi) * 272 + 16 * g4;
; #pragma unroll
;                     for (int s = 0; s < 4; ++s) { const bf16x8 a = *(const bf16x8*)(ka + 64 * s);
;                         sA[k4] = __builtin_amdgcn_mfma_f32_16x16x32_bf16(a, bqA[s], sA[k4], 0, 0, 0); sB[k4] = __builtin_amdgcn_mfma_f32_16x16x32_bf16(a, bqB[s], sB[k4], 0, 0, 0); } } }
.LBB0_463:
	ds_read_b128 v[132:135], v206 offset:34816
	ds_read_b128 v[136:139], v206 offset:34880
	s_mov_b64 s[14:15], -1
	s_and_b64 vcc, exec, s[6:7]
	s_waitcnt lgkmcnt(1)
	v_mfma_f32_16x16x32_bf16 v[140:143], v[132:135], v[64:67], 0
	v_mfma_f32_16x16x32_bf16 v[132:135], v[132:135], v[56:59], 0
	s_waitcnt lgkmcnt(0)
	v_mfma_f32_16x16x32_bf16 v[140:143], v[136:139], v[60:63], v[140:143]
	v_mfma_f32_16x16x32_bf16 v[132:135], v[136:139], v[52:55], v[132:135]
	ds_read_b128 v[136:139], v206 offset:34944
	ds_read_b128 v[144:147], v206 offset:35008
	s_waitcnt lgkmcnt(1)
	v_mfma_f32_16x16x32_bf16 v[140:143], v[136:139], v[48:51], v[140:143]
	v_mfma_f32_16x16x32_bf16 v[132:135], v[136:139], v[40:43], v[132:135]
	s_waitcnt lgkmcnt(0)
	v_mfma_f32_16x16x32_bf16 v[140:143], v[144:147], v[44:47], v[140:143]
	v_mfma_f32_16x16x32_bf16 v[132:135], v[144:147], v[36:39], v[132:135]
	ds_read_b128 v[136:139], v206 offset:39168
	ds_read_b128 v[144:147], v206 offset:39232
	s_waitcnt lgkmcnt(1)
	v_mfma_f32_16x16x32_bf16 v[188:191], v[136:139], v[64:67], 0
	v_mfma_f32_16x16x32_bf16 v[136:139], v[136:139], v[56:59], 0
	s_waitcnt lgkmcnt(0)
	v_mfma_f32_16x16x32_bf16 v[188:191], v[144:147], v[60:63], v[188:191]
	v_mfma_f32_16x16x32_bf16 v[136:139], v[144:147], v[52:55], v[136:139]
	ds_read_b128 v[144:147], v206 offset:39296
	ds_read_b128 v[244:247], v206 offset:39360
	s_waitcnt lgkmcnt(1)
	v_mfma_f32_16x16x32_bf16 v[188:191], v[144:147], v[48:51], v[188:191]
	v_mfma_f32_16x16x32_bf16 v[136:139], v[144:147], v[40:43], v[136:139]
	s_waitcnt lgkmcnt(0)
	v_mfma_f32_16x16x32_bf16 v[144:147], v[244:247], v[44:47], v[188:191]
	v_mfma_f32_16x16x32_bf16 v[136:139], v[244:247], v[36:39], v[136:139]
	s_cbranch_vccnz .LBB0_465
	v_max3_f32 v2, v140, v141, v142
	v_max3_f32 v2, v2, v143, s95
	s_mov_b64 s[14:15], 0
	s_nop 2
	v_max3_f32 v3, v144, v145, v146
	v_max3_f32 v243, v2, v3, v147

; __device__ __forceinline__ void attn_item(const Params& p, unsigned char* lds, int item) {
;     ...
;         for (int ch = 0; ch < 8; ++ch) if (2 * ch < nkt) {
;             f32x4 sA[2], sB[2];
; #pragma unroll
;             for (int k4 = 0; k4 < 2; ++k4) { sA[k4] = (f32x4){0.f, 0.f, 0.f, 0.f}; sB[k4] = (f32x4){0.f, 0.f, 0.f, 0.f};
;                 if (2 * ch + k4 < nkt) { const unsigned char* ka = lds + AT_K + (16 * (2 * ch + k4) + qi) * 272 + 16 * g4;
; #pragma unroll
;                     for (int s = 0; s < 4; ++s) { const bf16x8 a = *(const bf16x8*)(ka + 64 * s);
;                         sA[k4] = __builtin_amdgcn_mfma_f32_16x16x32_bf16(a, bqA[s], sA[k4], 0, 0, 0); sB[k4] = __builtin_amdgcn_mfma_f32_16x16x32_bf16(a, bqB[s], sB[k4], 0, 0, 0); } } }
.LBB0_482:
	ds_read_b128 v[132:135], v206 offset:43520
	ds_read_b128 v[136:139], v206 offset:43584
	s_mov_b64 s[14:15], -1
	s_and_b64 vcc, exec, s[6:7]
	s_waitcnt lgkmcnt(1)
	v_mfma_f32_16x16x32_bf16 v[140:143], v[132:135], v[64:67], 0
	v_mfma_f32_16x16x32_bf16 v[132:135], v[132:135], v[56:59], 0
	s_waitcnt lgkmcnt(0)
	v_mfma_f32_16x16x32_bf16 v[140:143], v[136:139], v[60:63], v[140:143]
	v_mfma_f32_16x16x32_bf16 v[132:135], v[136:139], v[52:55], v[132:135]
	ds_read_b128 v[136:139], v206 offset:43648
	ds_read_b128 v[144:147], v206 offset:43712
	s_waitcnt lgkmcnt(1)
	v_mfma_f32_16x16x32_bf16 v[140:143], v[136:139], v[48:51], v[140:143]
	v_mfma_f32_16x16x32_bf16 v[132:135], v[136:139], v[40:43], v[132:135]
	s_waitcnt lgkmcnt(0)
	v_mfma_f32_16x16x32_bf16 v[140:143], v[144:147], v[44:47], v[140:143]
	v_mfma_f32_16x16x32_bf16 v[132:135], v[144:147], v[36:39], v[132:135]
	ds_read_b128 v[136:139], v206 offset:47872
	ds_read_b128 v[144:147], v206 offset:47936
	s_waitcnt lgkmcnt(1)
	v_mfma_f32_16x16x32_bf16 v[188:191], v[136:139], v[64:67], 0
	v_mfma_f32_16x16x32_bf16 v[136:139], v[136:139], v[56:59], 0
	s_waitcnt lgkmcnt(0)
	v_mfma_f32_16x16x32_bf16 v[188:191], v[144:147], v[60:63], v[188:191]
	v_mfma_f32_16x16x32_bf16 v[136:139], v[144:147], v[52:55], v[136:139]
	ds_read_b128 v[144:147], v206 offset:48000
	ds_read_b128 v[244:247], v206 offset:48064
	s_waitcnt lgkmcnt(1)
	v_mfma_f32_16x16x32_bf16 v[188:191], v[144:147], v[48:51], v[188:191]
	v_mfma_f32_16x16x32_bf16 v[136:139], v[144:147], v[40:43], v[136:139]
	s_waitcnt lgkmcnt(0)
	v_mfma_f32_16x16x32_bf16 v[144:147], v[244:247], v[44:47], v[188:191]
	v_mfma_f32_16x16x32_bf16 v[136:139], v[244:247], v[36:39], v[136:139]
	s_cbranch_vccnz .LBB0_484
	v_max3_f32 v2, v140, v141, v142
	v_max3_f32 v2, v2, v143, s95
	s_mov_b64 s[14:15], 0
	s_nop 2
	v_max3_f32 v3, v144, v145, v146
	v_max3_f32 v243, v2, v3, v147

; __device__ __forceinline__ void attn_item(const Params& p, unsigned char* lds, int item) {
;     ...
;         for (int ch = 0; ch < 8; ++ch) if (2 * ch < nkt) {
;             f32x4 sA[2], sB[2];
; #pragma unroll
;             for (int k4 = 0; k4 < 2; ++k4) { sA[k4] = (f32x4){0.f, 0.f, 0.f, 0.f}; sB[k4] = (f32x4){0.f, 0.f, 0.f, 0.f};
;                 if (2 * ch + k4 < nkt) { const unsigned char* ka = lds + AT_K + (16 * (2 * ch + k4) + qi) * 272 + 16 * g4;
; #pragma unroll
;                     for (int s = 0; s < 4; ++s) { const bf16x8 a = *(const bf16x8*)(ka + 64 * s);
;                         sA[k4] = __builtin_amdgcn_mfma_f32_16x16x32_bf16(a, bqA[s], sA[k4], 0, 0, 0); sB[k4] = __builtin_amdgcn_mfma_f32_16x16x32_bf16(a, bqB[s], sB[k4], 0, 0, 0); } } }
.LBB0_501:
	ds_read_b128 v[132:135], v206 offset:52224
	ds_read_b128 v[136:139], v206 offset:52288
	s_mov_b64 s[14:15], -1
	s_and_b64 vcc, exec, s[6:7]
	s_waitcnt lgkmcnt(1)
	v_mfma_f32_16x16x32_bf16 v[140:143], v[132:135], v[64:67], 0
	v_mfma_f32_16x16x32_bf16 v[132:135], v[132:135], v[56:59], 0
	s_waitcnt lgkmcnt(0)
	v_mfma_f32_16x16x32_bf16 v[140:143], v[136:139], v[60:63], v[140:143]
	v_mfma_f32_16x16x32_bf16 v[132:135], v[136:139], v[52:55], v[132:135]
	ds_read_b128 v[136:139], v206 offset:52352
	ds_read_b128 v[144:147], v206 offset:52416
	s_waitcnt lgkmcnt(1)
	v_mfma_f32_16x16x32_bf16 v[140:143], v[136:139], v[48:51], v[140:143]
	v_mfma_f32_16x16x32_bf16 v[132:135], v[136:139], v[40:43], v[132:135]
	s_waitcnt lgkmcnt(0)
	v_mfma_f32_16x16x32_bf16 v[140:143], v[144:147], v[44:47], v[140:143]
	v_mfma_f32_16x16x32_bf16 v[132:135], v[144:147], v[36:39], v[132:135]
	ds_read_b128 v[136:139], v206 offset:56576
	ds_read_b128 v[144:147], v206 offset:56640
	s_waitcnt lgkmcnt(1)
	v_mfma_f32_16x16x32_bf16 v[188:191], v[136:139], v[64:67], 0
	v_mfma_f32_16x16x32_bf16 v[136:139], v[136:139], v[56:59], 0
	s_waitcnt lgkmcnt(0)
	v_mfma_f32_16x16x32_bf16 v[188:191], v[144:147], v[60:63], v[188:191]
	v_mfma_f32_16x16x32_bf16 v[136:139], v[144:147], v[52:55], v[136:139]
	ds_read_b128 v[144:147], v206 offset:56704
	ds_read_b128 v[244:247], v206 offset:56768
	s_waitcnt lgkmcnt(1)
	v_mfma_f32_16x16x32_bf16 v[188:191], v[144:147], v[48:51], v[188:191]
	v_mfma_f32_16x16x32_bf16 v[136:139], v[144:147], v[40:43], v[136:139]
	s_waitcnt lgkmcnt(0)
	v_mfma_f32_16x16x32_bf16 v[144:147], v[244:247], v[44:47], v[188:191]
	v_mfma_f32_16x16x32_bf16 v[136:139], v[244:247], v[36:39], v[136:139]
	s_cbranch_vccnz .LBB0_503
	v_max3_f32 v2, v140, v141, v142
	v_max3_f32 v2, v2, v143, s95
	s_mov_b64 s[14:15], 0
	s_nop 2
	v_max3_f32 v3, v144, v145, v146
	v_max3_f32 v243, v2, v3, v147

; __device__ __forceinline__ void attn_item(const Params& p, unsigned char* lds, int item) {
;     ...
;         for (int ch = 0; ch < 8; ++ch) if (2 * ch < nkt) {
;             f32x4 sA[2], sB[2];
; #pragma unroll
;             for (int k4 = 0; k4 < 2; ++k4) { sA[k4] = (f32x4){0.f, 0.f, 0.f, 0.f}; sB[k4] = (f32x4){0.f, 0.f, 0.f, 0.f};
;                 if (2 * ch + k4 < nkt) { const unsigned char* ka = lds + AT_K + (16 * (2 * ch + k4) + qi) * 272 + 16 * g4;
; #pragma unroll
;                     for (int s = 0; s < 4; ++s) { const bf16x8 a = *(const bf16x8*)(ka + 64 * s);
;                         sA[k4] = __builtin_amdgcn_mfma_f32_16x16x32_bf16(a, bqA[s], sA[k4], 0, 0, 0); sB[k4] = __builtin_amdgcn_mfma_f32_16x16x32_bf16(a, bqB[s], sB[k4], 0, 0, 0); } } }
.LBB0_520:
	ds_read_b128 v[132:135], v206 offset:60928
	ds_read_b128 v[136:139], v206 offset:60992
	s_mov_b64 s[10:11], -1
	s_and_b64 vcc, exec, s[6:7]
	s_waitcnt lgkmcnt(1)
	v_mfma_f32_16x16x32_bf16 v[140:143], v[132:135], v[64:67], 0
	v_mfma_f32_16x16x32_bf16 v[132:135], v[132:135], v[56:59], 0
	s_waitcnt lgkmcnt(0)
	v_mfma_f32_16x16x32_bf16 v[140:143], v[136:139], v[60:63], v[140:143]
	v_mfma_f32_16x16x32_bf16 v[132:135], v[136:139], v[52:55], v[132:135]
	ds_read_b128 v[136:139], v206 offset:61056
	ds_read_b128 v[144:147], v206 offset:61120
	s_waitcnt lgkmcnt(1)
	v_mfma_f32_16x16x32_bf16 v[140:143], v[136:139], v[48:51], v[140:143]
	v_mfma_f32_16x16x32_bf16 v[132:135], v[136:139], v[40:43], v[132:135]
	s_waitcnt lgkmcnt(0)
	v_mfma_f32_16x16x32_bf16 v[136:139], v[144:147], v[44:47], v[140:143]
	v_mfma_f32_16x16x32_bf16 v[132:135], v[144:147], v[36:39], v[132:135]
	s_nop 3
	ds_read_b128 v[140:143], v206 offset:65280
	ds_read_b128 v[144:147], v206 offset:65344
	s_waitcnt lgkmcnt(1)
	v_mfma_f32_16x16x32_bf16 v[64:67], v[140:143], v[64:67], 0
	v_mfma_f32_16x16x32_bf16 v[56:59], v[140:143], v[56:59], 0
	s_waitcnt lgkmcnt(0)
	v_mfma_f32_16x16x32_bf16 v[60:63], v[144:147], v[60:63], v[64:67]
	v_mfma_f32_16x16x32_bf16 v[52:55], v[144:147], v[52:55], v[56:59]
	s_nop 4
	ds_read_b128 v[56:59], v206 offset:65408
	ds_read_b128 v[64:67], v206 offset:65472
	s_waitcnt lgkmcnt(1)
	v_mfma_f32_16x16x32_bf16 v[48:51], v[56:59], v[48:51], v[60:63]
	v_mfma_f32_16x16x32_bf16 v[52:55], v[56:59], v[40:43], v[52:55]
	s_waitcnt lgkmcnt(0)
	v_mfma_f32_16x16x32_bf16 v[40:43], v[64:67], v[44:47], v[48:51]
	v_mfma_f32_16x16x32_bf16 v[36:39], v[64:67], v[36:39], v[52:55]
	s_cbranch_vccnz .LBB0_522
	v_max3_f32 v2, v136, v137, v138
	v_max3_f32 v2, v2, v139, s95
	s_mov_b64 s[10:11], 0
	s_nop 2
	v_max3_f32 v3, v40, v41, v42
	v_max3_f32 v50, v2, v3, v43
	v_mov_b32_e32 v45, v43
	v_mov_b32_e32 v44, v42
	v_mov_b32_e32 v3, v41
	v_mov_b32_e32 v2, v40
	v_mov_b32_e32 v47, v139
	v_mov_b32_e32 v46, v138
	v_mov_b32_e32 v49, v137
	v_mov_b32_e32 v48, v136
